# system-scope streaming policy (sc0 sc1 nt) on the P0 weight-transposition input loads (read-once f32 weights)
# speedup vs baseline: 1.0470x; 1.0090x over previous
; DI unsigned pk2(float a, float b) { f32x2 v = {a, b}; bf16x2v r = __builtin_convertvector(v, bf16x2v); return __builtin_bit_cast(unsigned, r); }
; DI void phase0(const Params& p, char* smem) {
;     ...
;     for (int u = blockIdx.x; u < 1280; u += gridDim.x) {
;         const float* src; int ld; bf16_t* dst;
;         if (u < 1024) { const int kt = u >> 6, nt = u & 63; src = p.w_in + (size_t)(kt * 64) * INW + nt * 64; ld = INW; dst = p.wtin + (size_t)(nt * 64) * DM + kt * 64; }
;         else { const int v = u - 1024, kt = v >> 4, nt = v & 15; src = p.w_out + (size_t)(kt * 64) * DM + nt * 64; ld = DM; dst = p.wtout + (size_t)(nt * 64) * DM + kt * 64; }
; #pragma unroll
;         for (int i = 0; i < 2; ++i) {
;             const int r = (tid >> 4) + 32 * i, c = (tid & 15) * 4;
;             const f32x4 v = *(const f32x4*)(src + (size_t)r * ld + c);
;             tile[r * 65 + c] = v[0]; tile[r * 65 + c + 1] = v[1]; tile[r * 65 + c + 2] = v[2]; tile[r * 65 + c + 3] = v[3];
;         }
;         __syncthreads();
;         {
;             const int n = (tid >> 3), kc = (tid & 7) * 8;
;             u32x4 w;
;             w[0] = pk2(tile[(kc + 0) * 65 + n], tile[(kc + 1) * 65 + n]);
;             w[1] = pk2(tile[(kc + 2) * 65 + n], tile[(kc + 3) * 65 + n]);
;             w[2] = pk2(tile[(kc + 4) * 65 + n], tile[(kc + 5) * 65 + n]);
;             w[3] = pk2(tile[(kc + 6) * 65 + n], tile[(kc + 7) * 65 + n]);
;             *(u32x4*)(dst + (size_t)n * DM + kc) = w;
;         }
;         __syncthreads();
;     }
.LBB0_8:
	s_and_b32 s4, s15, s4
	s_lshl_b32 s13, s4, 2
	s_add_u32 s10, s10, s13
	s_addc_u32 s11, s11, 0
	v_lshl_add_u64 v[18:19], s[10:11], 0, v[4:5]
	v_mad_i64_i32 v[14:15], s[10:11], s12, v2, 0
	v_lshl_add_u64 v[14:15], v[14:15], 2, v[18:19]
	global_load_dwordx4 v[14:17], v[14:15], off sc0 sc1 nt
	v_mad_i64_i32 v[20:21], s[10:11], s12, v8, 0
	v_lshl_add_u64 v[18:19], v[20:21], 2, v[18:19]
	global_load_dwordx4 v[18:21], v[18:19], off sc0 sc1 nt
	s_lshl_b32 s4, s4, 11
	s_add_u32 s4, s8, s4
	s_addc_u32 s8, s9, 0
	s_lshl_b64 s[6:7], s[6:7], 1
	s_add_u32 s6, s4, s6
	s_addc_u32 s7, s8, s7
	s_add_i32 s19, s19, s14
	s_add_i32 s15, s15, s16
	s_add_i32 s17, s17, s18
	v_lshl_add_u64 v[22:23], s[6:7], 0, v[6:7]
	s_cmpk_gt_i32 s19, 0x4ff
	v_lshl_add_u64 v[22:23], v[22:23], 0, v[10:11]
	s_waitcnt vmcnt(1)
	ds_write2_b32 v3, v14, v15 offset1:1
	ds_write2_b32 v3, v16, v17 offset0:2 offset1:3
	s_waitcnt vmcnt(0)
	ds_write2_b32 v9, v18, v19 offset1:1
	ds_write2_b32 v12, v20, v21 offset1:1
	s_waitcnt lgkmcnt(0)
	s_barrier
	ds_read2_b32 v[14:15], v1 offset1:65
	ds_read2_b32 v[16:17], v1 offset0:130 offset1:195
	ds_read2_b32 v[18:19], v13 offset0:4 offset1:69
	ds_read2_b32 v[20:21], v13 offset0:134 offset1:199
	s_waitcnt lgkmcnt(3)
	v_cvt_pk_bf16_f32 v14, v14, v15
	s_waitcnt lgkmcnt(2)
	v_cvt_pk_bf16_f32 v15, v16, v17
	s_waitcnt lgkmcnt(1)
	v_cvt_pk_bf16_f32 v16, v18, v19
	s_waitcnt lgkmcnt(0)
	v_cvt_pk_bf16_f32 v17, v20, v21
	global_store_dwordx4 v[22:23], v[14:17], off
	s_barrier
	s_cbranch_scc1 .LBB0_13

; DI void phase0(const Params& p, char* smem) {
;     ...
;     for (int u = blockIdx.x; u < 1280; u += gridDim.x) {
;         const float* src; int ld; bf16_t* dst;
;         if (u < 1024) { const int kt = u >> 6, nt = u & 63; src = p.w_in + (size_t)(kt * 64) * INW + nt * 64; ld = INW; dst = p.wtin + (size_t)(nt * 64) * DM + kt * 64; }
;         else { const int v = u - 1024, kt = v >> 4, nt = v & 15; src = p.w_out + (size_t)(kt * 64) * DM + nt * 64; ld = DM; dst = p.wtout + (size_t)(nt * 64) * DM + kt * 64; }
; #pragma unroll
;         for (int i = 0; i < 2; ++i) {
;             const int r = (tid >> 4) + 32 * i, c = (tid & 15) * 4;
;             const f32x4 v = *(const f32x4*)(src + (size_t)r * ld + c);
.Lp0t_ld_0:
	s_and_b32 s4, s15, s4
	s_lshl_b32 s13, s4, 2
	s_add_u32 s10, s10, s13
	s_addc_u32 s11, s11, 0
	v_lshl_add_u64 v[18:19], s[10:11], 0, v[4:5]
	v_mad_i64_i32 v[14:15], s[10:11], s12, v2, 0
	v_lshl_add_u64 v[14:15], v[14:15], 2, v[18:19]
	global_load_dwordx4 v[24:27], v[14:15], off sc0 sc1 nt
	v_mad_i64_i32 v[20:21], s[10:11], s12, v8, 0
	v_lshl_add_u64 v[18:19], v[20:21], 2, v[18:19]
	global_load_dwordx4 v[28:31], v[18:19], off sc0 sc1 nt
	s_lshl_b32 s4, s4, 11
	s_add_u32 s4, s8, s4
	s_addc_u32 s8, s9, 0
	s_lshl_b64 s[6:7], s[6:7], 1
	s_add_u32 s6, s4, s6
	s_addc_u32 s7, s8, s7
	s_add_i32 s19, s19, s14
	s_add_i32 s15, s15, s16
	s_add_i32 s17, s17, s18
	v_lshl_add_u64 v[68:69], s[6:7], 0, v[6:7]
	v_lshl_add_u64 v[68:69], v[68:69], 0, v[10:11]
	s_bitset1_b32 s20, 0
	s_cmpk_gt_i32 s19, 0x4ff
	s_cbranch_scc1 .Lp0t_issued
	s_cmpk_gt_i32 s19, 0x3ff
	s_cbranch_scc0 .Lp0t_win_1
	s_and_b32 s4, s17, 0x7fffffc0
	s_addk_i32 s4, 0xf000
	s_lshl_b64 s[6:7], s[4:5], 12
	s_add_u32 s10, s50, s6
	s_addc_u32 s11, s51, s7
	s_mov_b64 s[6:7], s[4:5]
	s_mov_b64 s[8:9], s[64:65]
	s_mov_b64 s[12:13], 0x400
	s_movk_i32 s4, 0x3c0
	s_branch .Lp0t_ld_1

; DI void phase0(const Params& p, char* smem) {
;     ...
;     for (int u = blockIdx.x; u < 1280; u += gridDim.x) {
;         const float* src; int ld; bf16_t* dst;
;         if (u < 1024) { const int kt = u >> 6, nt = u & 63; src = p.w_in + (size_t)(kt * 64) * INW + nt * 64; ld = INW; dst = p.wtin + (size_t)(nt * 64) * DM + kt * 64; }
;         else { const int v = u - 1024, kt = v >> 4, nt = v & 15; src = p.w_out + (size_t)(kt * 64) * DM + nt * 64; ld = DM; dst = p.wtout + (size_t)(nt * 64) * DM + kt * 64; }
; #pragma unroll
;         for (int i = 0; i < 2; ++i) {
;             const int r = (tid >> 4) + 32 * i, c = (tid & 15) * 4;
;             const f32x4 v = *(const f32x4*)(src + (size_t)r * ld + c);
.Lp0t_ld_1:
	s_and_b32 s4, s15, s4
	s_lshl_b32 s13, s4, 2
	s_add_u32 s10, s10, s13
	s_addc_u32 s11, s11, 0
	v_lshl_add_u64 v[18:19], s[10:11], 0, v[4:5]
	v_mad_i64_i32 v[14:15], s[10:11], s12, v2, 0
	v_lshl_add_u64 v[14:15], v[14:15], 2, v[18:19]
	global_load_dwordx4 v[32:35], v[14:15], off sc0 sc1 nt
	v_mad_i64_i32 v[20:21], s[10:11], s12, v8, 0
	v_lshl_add_u64 v[18:19], v[20:21], 2, v[18:19]
	global_load_dwordx4 v[36:39], v[18:19], off sc0 sc1 nt
	s_lshl_b32 s4, s4, 11
	s_add_u32 s4, s8, s4
	s_addc_u32 s8, s9, 0
	s_lshl_b64 s[6:7], s[6:7], 1
	s_add_u32 s6, s4, s6
	s_addc_u32 s7, s8, s7
	s_add_i32 s19, s19, s14
	s_add_i32 s15, s15, s16
	s_add_i32 s17, s17, s18
	v_lshl_add_u64 v[70:71], s[6:7], 0, v[6:7]
	v_lshl_add_u64 v[70:71], v[70:71], 0, v[10:11]
	s_bitset1_b32 s20, 1
	s_cmpk_gt_i32 s19, 0x4ff
	s_cbranch_scc1 .Lp0t_issued
	s_cmpk_gt_i32 s19, 0x3ff
	s_cbranch_scc0 .Lp0t_win_2
	s_and_b32 s4, s17, 0x7fffffc0
	s_addk_i32 s4, 0xf000
	s_lshl_b64 s[6:7], s[4:5], 12
	s_add_u32 s10, s50, s6
	s_addc_u32 s11, s51, s7
	s_mov_b64 s[6:7], s[4:5]
	s_mov_b64 s[8:9], s[64:65]
	s_mov_b64 s[12:13], 0x400
	s_movk_i32 s4, 0x3c0
	s_branch .Lp0t_ld_2

; DI void phase0(const Params& p, char* smem) {
;     ...
;     for (int u = blockIdx.x; u < 1280; u += gridDim.x) {
;         const float* src; int ld; bf16_t* dst;
;         if (u < 1024) { const int kt = u >> 6, nt = u & 63; src = p.w_in + (size_t)(kt * 64) * INW + nt * 64; ld = INW; dst = p.wtin + (size_t)(nt * 64) * DM + kt * 64; }
;         else { const int v = u - 1024, kt = v >> 4, nt = v & 15; src = p.w_out + (size_t)(kt * 64) * DM + nt * 64; ld = DM; dst = p.wtout + (size_t)(nt * 64) * DM + kt * 64; }
; #pragma unroll
;         for (int i = 0; i < 2; ++i) {
;             const int r = (tid >> 4) + 32 * i, c = (tid & 15) * 4;
;             const f32x4 v = *(const f32x4*)(src + (size_t)r * ld + c);
.Lp0t_ld_2:
	s_and_b32 s4, s15, s4
	s_lshl_b32 s13, s4, 2
	s_add_u32 s10, s10, s13
	s_addc_u32 s11, s11, 0
	v_lshl_add_u64 v[18:19], s[10:11], 0, v[4:5]
	v_mad_i64_i32 v[14:15], s[10:11], s12, v2, 0
	v_lshl_add_u64 v[14:15], v[14:15], 2, v[18:19]
	global_load_dwordx4 v[40:43], v[14:15], off sc0 sc1 nt
	v_mad_i64_i32 v[20:21], s[10:11], s12, v8, 0
	v_lshl_add_u64 v[18:19], v[20:21], 2, v[18:19]
	global_load_dwordx4 v[44:47], v[18:19], off sc0 sc1 nt
	s_lshl_b32 s4, s4, 11
	s_add_u32 s4, s8, s4
	s_addc_u32 s8, s9, 0
	s_lshl_b64 s[6:7], s[6:7], 1
	s_add_u32 s6, s4, s6
	s_addc_u32 s7, s8, s7
	s_add_i32 s19, s19, s14
	s_add_i32 s15, s15, s16
	s_add_i32 s17, s17, s18
	v_lshl_add_u64 v[72:73], s[6:7], 0, v[6:7]
	v_lshl_add_u64 v[72:73], v[72:73], 0, v[10:11]
	s_bitset1_b32 s20, 2
	s_cmpk_gt_i32 s19, 0x4ff
	s_cbranch_scc1 .Lp0t_issued
	s_cmpk_gt_i32 s19, 0x3ff
	s_cbranch_scc0 .Lp0t_win_3
	s_and_b32 s4, s17, 0x7fffffc0
	s_addk_i32 s4, 0xf000
	s_lshl_b64 s[6:7], s[4:5], 12
	s_add_u32 s10, s50, s6
	s_addc_u32 s11, s51, s7
	s_mov_b64 s[6:7], s[4:5]
	s_mov_b64 s[8:9], s[64:65]
	s_mov_b64 s[12:13], 0x400
	s_movk_i32 s4, 0x3c0
	s_branch .Lp0t_ld_3

; DI void phase0(const Params& p, char* smem) {
;     ...
;     for (int u = blockIdx.x; u < 1280; u += gridDim.x) {
;         const float* src; int ld; bf16_t* dst;
;         if (u < 1024) { const int kt = u >> 6, nt = u & 63; src = p.w_in + (size_t)(kt * 64) * INW + nt * 64; ld = INW; dst = p.wtin + (size_t)(nt * 64) * DM + kt * 64; }
;         else { const int v = u - 1024, kt = v >> 4, nt = v & 15; src = p.w_out + (size_t)(kt * 64) * DM + nt * 64; ld = DM; dst = p.wtout + (size_t)(nt * 64) * DM + kt * 64; }
; #pragma unroll
;         for (int i = 0; i < 2; ++i) {
;             const int r = (tid >> 4) + 32 * i, c = (tid & 15) * 4;
;             const f32x4 v = *(const f32x4*)(src + (size_t)r * ld + c);
.Lp0t_ld_3:
	s_and_b32 s4, s15, s4
	s_lshl_b32 s13, s4, 2
	s_add_u32 s10, s10, s13
	s_addc_u32 s11, s11, 0
	v_lshl_add_u64 v[18:19], s[10:11], 0, v[4:5]
	v_mad_i64_i32 v[14:15], s[10:11], s12, v2, 0
	v_lshl_add_u64 v[14:15], v[14:15], 2, v[18:19]
	global_load_dwordx4 v[52:55], v[14:15], off sc0 sc1 nt
	v_mad_i64_i32 v[20:21], s[10:11], s12, v8, 0
	v_lshl_add_u64 v[18:19], v[20:21], 2, v[18:19]
	global_load_dwordx4 v[56:59], v[18:19], off sc0 sc1 nt
	s_lshl_b32 s4, s4, 11
	s_add_u32 s4, s8, s4
	s_addc_u32 s8, s9, 0
	s_lshl_b64 s[6:7], s[6:7], 1
	s_add_u32 s6, s4, s6
	s_addc_u32 s7, s8, s7
	s_add_i32 s19, s19, s14
	s_add_i32 s15, s15, s16
	s_add_i32 s17, s17, s18
	v_lshl_add_u64 v[74:75], s[6:7], 0, v[6:7]
	v_lshl_add_u64 v[74:75], v[74:75], 0, v[10:11]
	s_bitset1_b32 s20, 3
	s_cmpk_gt_i32 s19, 0x4ff
	s_cbranch_scc1 .Lp0t_issued
	s_cmpk_gt_i32 s19, 0x3ff
	s_cbranch_scc0 .Lp0t_win_4
	s_and_b32 s4, s17, 0x7fffffc0
	s_addk_i32 s4, 0xf000
	s_lshl_b64 s[6:7], s[4:5], 12
	s_add_u32 s10, s50, s6
	s_addc_u32 s11, s51, s7
	s_mov_b64 s[6:7], s[4:5]
	s_mov_b64 s[8:9], s[64:65]
	s_mov_b64 s[12:13], 0x400
	s_movk_i32 s4, 0x3c0
	s_branch .Lp0t_ld_4

; DI void phase0(const Params& p, char* smem) {
;     ...
;     for (int u = blockIdx.x; u < 1280; u += gridDim.x) {
;         const float* src; int ld; bf16_t* dst;
;         if (u < 1024) { const int kt = u >> 6, nt = u & 63; src = p.w_in + (size_t)(kt * 64) * INW + nt * 64; ld = INW; dst = p.wtin + (size_t)(nt * 64) * DM + kt * 64; }
;         else { const int v = u - 1024, kt = v >> 4, nt = v & 15; src = p.w_out + (size_t)(kt * 64) * DM + nt * 64; ld = DM; dst = p.wtout + (size_t)(nt * 64) * DM + kt * 64; }
; #pragma unroll
;         for (int i = 0; i < 2; ++i) {
;             const int r = (tid >> 4) + 32 * i, c = (tid & 15) * 4;
;             const f32x4 v = *(const f32x4*)(src + (size_t)r * ld + c);
.Lp0t_ld_4:
	s_and_b32 s4, s15, s4
	s_lshl_b32 s13, s4, 2
	s_add_u32 s10, s10, s13
	s_addc_u32 s11, s11, 0
	v_lshl_add_u64 v[18:19], s[10:11], 0, v[4:5]
	v_mad_i64_i32 v[14:15], s[10:11], s12, v2, 0
	v_lshl_add_u64 v[14:15], v[14:15], 2, v[18:19]
	global_load_dwordx4 v[60:63], v[14:15], off sc0 sc1 nt
	v_mad_i64_i32 v[20:21], s[10:11], s12, v8, 0
	v_lshl_add_u64 v[18:19], v[20:21], 2, v[18:19]
	global_load_dwordx4 v[64:67], v[18:19], off sc0 sc1 nt
	s_lshl_b32 s4, s4, 11
	s_add_u32 s4, s8, s4
	s_addc_u32 s8, s9, 0
	s_lshl_b64 s[6:7], s[6:7], 1
	s_add_u32 s6, s4, s6
	s_addc_u32 s7, s8, s7
	s_add_i32 s19, s19, s14
	s_add_i32 s15, s15, s16
	s_add_i32 s17, s17, s18
	v_lshl_add_u64 v[76:77], s[6:7], 0, v[6:7]
	v_lshl_add_u64 v[76:77], v[76:77], 0, v[10:11]
	s_bitset1_b32 s20, 4
